# prologue input rms-norm: norm weight chunks hoisted out of the row loop, stores no longer drained per chunk
# baseline (speedup 1.0000x reference)
; __device__ __forceinline__ unsigned pk2(float lo, float hi) { f32x2 v = {lo, hi}; bf16x2_t b = __builtin_convertvector(v, bf16x2_t); return __builtin_bit_cast(unsigned, b); }
; #define FIN(i) ((const float*)(const GAS float*)(((const float* const __attribute__((address_space(4)))*)__builtin_amdgcn_kernarg_segment_ptr())[i]))
; __device__ __forceinline__ void rms_row_to_bf16(const float* xrow, const float* g, bf16_t* orow, int lane) {
;     const f32x4* xr = (const f32x4*)xrow + lane; const f32x4* gr = (const f32x4*)g + lane;
;     f32x4 v[8]; float s = 0.f;
; #pragma unroll
;     for (int j = 0; j < 8; ++j) { v[j] = xr[64 * j]; s += (v[j].x * v[j].x + v[j].y * v[j].y) + (v[j].z * v[j].z + v[j].w * v[j].w); }
;     const float rstd = 1.f / sqrtf(wave_sum(s) * (1.f / DM) + EPS);
;     u32x2* o8 = (u32x2*)orow + lane;
; #pragma unroll
;     for (int j = 0; j < 8; ++j) { const f32x4 gg = gr[64 * j]; u32x2 w; w.x = pk2(v[j].x * rstd * gg.x, v[j].y * rstd * gg.y); w.y = pk2(v[j].z * rstd * gg.z, v[j].w * rstd * gg.w); o8[64 * j] = w; }
; __device__ __forceinline__ void phase_prologue(Frame& F) {
;     ...
;     bf16_t* H = (bf16_t*)(F.ws + WS_H);
;     for (int m = F.gw; m < MROWS; m += F.ngw) rms_row_to_bf16(x_row_l0(F, m), FIN(IN_GPRE), H + (size_t)m * DM, lane);
.LBB0_83:
	v_readlane_b32 s4, v252, 12
	v_readlane_b32 s5, v252, 13
	s_or_b64 exec, exec, s[4:5]
	v_readlane_b32 s48, v252, 8
	s_cmpk_gt_i32 s14, 0x201f
	s_mov_b32 s92, s80
	v_readlane_b32 s49, v252, 9
	s_cbranch_scc1 .LBB0_86
	s_ashr_i32 s15, s14, 31
	s_load_dwordx4 s[8:11], s[0:1], 0x0
	s_lshl_b64 s[4:5], s[14:15], 12
	v_readlane_b32 s6, v252, 10
	v_readlane_b32 s7, v252, 11
	s_add_u32 s4, s6, s4
	v_mbcnt_lo_u32_b32 v1, -1, 0
	v_mov_b32_e32 v67, 0
	s_addc_u32 s5, s7, s5
	v_mbcnt_hi_u32_b32 v1, -1, v1
	v_lshl_add_u64 v[4:5], s[4:5], 0, v[66:67]
	s_mov_b64 s[4:5], 0xa700000
	s_ashr_i32 s89, s88, 31
	v_and_b32_e32 v6, 64, v1
	v_lshl_add_u64 v[4:5], v[4:5], 0, s[4:5]
	s_lshl_b64 s[4:5], s[88:89], 12
	v_mov_b32_e32 v3, v67
	s_movk_i32 s3, 0x1000
	v_add_u32_e32 v6, 64, v6
	v_xor_b32_e32 v7, 1, v1
	v_xor_b32_e32 v8, 2, v1
	v_xor_b32_e32 v9, 4, v1
	v_xor_b32_e32 v10, 8, v1
	v_xor_b32_e32 v11, 16, v1
	v_xor_b32_e32 v12, 32, v1
	v_mov_b32_e32 v13, 0x358637bd
	s_mov_b32 s18, 0xf800000
	v_mov_b32_e32 v14, 0x260
	s_load_dwordx2 s[12:13], s[0:1], 0x38
	s_waitcnt lgkmcnt(0)
	v_lshl_add_u64 v[132:133], s[12:13], 0, v[2:3]
	global_load_dwordx4 v[100:103], v2, s[12:13]
	v_add_co_u32_e32 v132, vcc, s3, v132
	global_load_dwordx4 v[104:107], v2, s[12:13] offset:1024
	v_addc_co_u32_e32 v133, vcc, 0, v133, vcc
	global_load_dwordx4 v[108:111], v2, s[12:13] offset:2048
	global_load_dwordx4 v[112:115], v2, s[12:13] offset:3072
	global_load_dwordx4 v[116:119], v[132:133], off
	global_load_dwordx4 v[120:123], v[132:133], off offset:1024
	global_load_dwordx4 v[124:127], v[132:133], off offset:2048
	global_load_dwordx4 v[128:131], v[132:133], off offset:3072
.LBB0_85:
	v_cmp_lt_i32_e32 vcc, v7, v6
	s_add_i32 s19, s14, 0xffffe000
	s_waitcnt lgkmcnt(0)
	s_mov_b64 s[6:7], s[8:9]
	v_cndmask_b32_e32 v15, v1, v7, vcc
	v_cmp_lt_i32_e32 vcc, v8, v6
	s_mov_b64 s[16:17], s[10:11]
	s_cmpk_lt_i32 s14, 0x2000
	v_cndmask_b32_e32 v16, v1, v8, vcc
	v_cmp_lt_i32_e32 vcc, v9, v6
	s_cselect_b32 s21, s15, 0
	s_cselect_b32 s20, s14, s19
	v_cndmask_b32_e32 v17, v1, v9, vcc
	v_cmp_lt_i32_e32 vcc, v10, v6
	s_cselect_b32 s17, s7, s17
	s_cselect_b32 s16, s6, s16
	v_cndmask_b32_e32 v18, v1, v10, vcc
	v_cmp_lt_i32_e32 vcc, v11, v6
	s_lshl_b64 s[6:7], s[20:21], 13
	s_add_u32 s6, s16, s6
	v_cndmask_b32_e32 v19, v1, v11, vcc
	v_cmp_lt_i32_e32 vcc, v12, v6
	s_addc_u32 s7, s17, s7
	v_cndmask_b32_e32 v20, v1, v12, vcc
	v_lshlrev_b32_e32 v70, 2, v16
	v_lshlrev_b32_e32 v71, 2, v17
	v_lshlrev_b32_e32 v72, 2, v18
	v_lshlrev_b32_e32 v73, 2, v19
	v_lshlrev_b32_e32 v74, 2, v20
	global_load_dwordx4 v[16:19], v2, s[6:7]
	global_load_dwordx4 v[20:23], v2, s[6:7] offset:1024
	global_load_dwordx4 v[24:27], v2, s[6:7] offset:2048
	global_load_dwordx4 v[28:31], v2, s[6:7] offset:3072
	v_lshl_add_u64 v[36:37], s[6:7], 0, v[2:3]
	v_add_co_u32_e32 v52, vcc, s3, v36
	v_addc_co_u32_e32 v53, vcc, 0, v37, vcc
	global_load_dwordx4 v[36:39], v[52:53], off
	global_load_dwordx4 v[40:43], v[52:53], off offset:1024
	global_load_dwordx4 v[44:47], v[52:53], off offset:3072
	global_load_dwordx4 v[48:51], v[52:53], off offset:2048
	v_lshlrev_b32_e32 v15, 2, v15
	s_add_u32 s14, s14, s88
	s_addc_u32 s15, s15, s89
	s_cmpk_lt_i32 s14, 0x2020
	s_waitcnt vmcnt(7)
	v_mov_b32_e32 v54, v17
	s_waitcnt vmcnt(6)
	v_mov_b32_e32 v55, v21
	v_mov_b32_e32 v58, v19
	v_mov_b32_e32 v59, v23
	v_mov_b32_e32 v52, v16
	v_mov_b32_e32 v53, v20
	v_mov_b32_e32 v56, v18
	v_mov_b32_e32 v57, v22
	s_waitcnt vmcnt(5)
	v_pk_mul_f32 v[60:61], v[26:27], v[26:27]
	v_pk_mul_f32 v[62:63], v[24:25], v[24:25]
	v_pk_mul_f32 v[54:55], v[54:55], v[54:55]
	v_pk_mul_f32 v[58:59], v[58:59], v[58:59]
	v_pk_mov_b32 v[68:69], v[62:63], v[60:61] op_sel:[1,0]
	v_mov_b32_e32 v63, v61
	v_pk_fma_f32 v[52:53], v[52:53], v[52:53], v[54:55]
	v_pk_fma_f32 v[54:55], v[56:57], v[56:57], v[58:59]
	s_waitcnt vmcnt(4)
	v_mul_f32_e32 v64, v29, v29
	v_mul_f32_e32 v66, v31, v31
	v_pk_add_f32 v[56:57], v[68:69], v[62:63]
	v_pk_add_f32 v[52:53], v[52:53], v[54:55]
	v_pk_fma_f32 v[60:61], v[28:29], v[28:29], v[64:65] op_sel_hi:[1,1,0]
	v_pk_fma_f32 v[64:65], v[30:31], v[30:31], v[66:67] op_sel_hi:[1,1,0]
	s_waitcnt vmcnt(3)
	v_mul_f32_e32 v69, v36, v36
	v_mul_f32_e32 v75, v37, v37
	v_pk_add_f32 v[54:55], v[56:57], v[56:57] op_sel:[0,1] op_sel_hi:[1,0]
	v_pk_add_f32 v[52:53], v[52:53], v[52:53] op_sel:[0,1] op_sel_hi:[1,0]
	v_mul_f32_e32 v61, v38, v38
	v_mul_f32_e32 v65, v39, v39
	s_waitcnt vmcnt(2)
	v_pk_mul_f32 v[58:59], v[42:43], v[42:43]
	v_pk_mul_f32 v[62:63], v[40:41], v[40:41]
	v_mov_b32_e32 v55, v75
	v_mov_b32_e32 v53, v69
	v_pk_mov_b32 v[56:57], v[62:63], v[58:59] op_sel:[1,0]
	v_mov_b32_e32 v63, v59
	v_pk_add_f32 v[60:61], v[60:61], v[64:65]
	v_pk_add_f32 v[52:53], v[52:53], v[54:55]
	s_waitcnt vmcnt(0)
; __device__ __forceinline__ unsigned pk2(float lo, float hi) { f32x2 v = {lo, hi}; bf16x2_t b = __builtin_convertvector(v, bf16x2_t); return __builtin_bit_cast(unsigned, b); }
; __device__ __forceinline__ float wave_sum(float v) {
; #pragma unroll
;     for (int o = 1; o < 64; o <<= 1) v += __shfl_xor(v, o);
;     return v;
; }
; __device__ __forceinline__ void rms_row_to_bf16(const float* xrow, const float* g, bf16_t* orow, int lane) {
;     ...
;     for (int j = 0; j < 8; ++j) { v[j] = xr[64 * j]; s += (v[j].x * v[j].x + v[j].y * v[j].y) + (v[j].z * v[j].z + v[j].w * v[j].w); }
;     const float rstd = 1.f / sqrtf(wave_sum(s) * (1.f / DM) + EPS);
;     u32x2* o8 = (u32x2*)orow + lane;
; #pragma unroll
;     for (int j = 0; j < 8; ++j) { const f32x4 gg = gr[64 * j]; u32x2 w; w.x = pk2(v[j].x * rstd * gg.x, v[j].y * rstd * gg.y); w.y = pk2(v[j].z * rstd * gg.z, v[j].w * rstd * gg.w); o8[64 * j] = w; }
	v_mul_f32_e32 v66, v49, v49
	v_mul_f32_e32 v68, v51, v51
	v_pk_add_f32 v[56:57], v[56:57], v[62:63]
	v_pk_add_f32 v[52:53], v[52:53], v[60:61]
	v_mul_f32_e32 v76, v44, v44
	v_mul_f32_e32 v77, v45, v45
	v_mul_f32_e32 v78, v46, v46
	v_mul_f32_e32 v79, v47, v47
	v_pk_fma_f32 v[58:59], v[48:49], v[48:49], v[66:67] op_sel_hi:[1,1,0]
	v_pk_fma_f32 v[66:67], v[50:51], v[50:51], v[68:69] op_sel_hi:[1,1,0]
	v_pk_add_f32 v[56:57], v[56:57], v[56:57] op_sel:[0,1] op_sel_hi:[1,0]
	v_pk_add_f32 v[52:53], v[52:53], v[52:53] op_sel:[0,1] op_sel_hi:[1,0]
	v_mov_b32_e32 v59, v78
	v_mov_b32_e32 v67, v79
	v_mov_b32_e32 v57, v77
	v_mov_b32_e32 v53, v76
	v_pk_add_f32 v[58:59], v[58:59], v[66:67]
	v_pk_add_f32 v[52:53], v[52:53], v[56:57]
	s_nop 0
	v_pk_add_f32 v[52:53], v[52:53], v[58:59]
	s_nop 0
	v_add_f32_e32 v52, v52, v53
	ds_bpermute_b32 v15, v15, v52
	s_waitcnt lgkmcnt(0)
	v_add_f32_e32 v15, v52, v15
	ds_bpermute_b32 v52, v70, v15
	s_waitcnt lgkmcnt(0)
	v_add_f32_e32 v15, v15, v52
	ds_bpermute_b32 v52, v71, v15
	s_waitcnt lgkmcnt(0)
	v_add_f32_e32 v15, v15, v52
	ds_bpermute_b32 v52, v72, v15
	s_waitcnt lgkmcnt(0)
	v_add_f32_e32 v15, v15, v52
	ds_bpermute_b32 v52, v73, v15
	s_waitcnt lgkmcnt(0)
	v_add_f32_e32 v15, v15, v52
	ds_bpermute_b32 v52, v74, v15
	s_waitcnt lgkmcnt(0)
	v_add_f32_e32 v15, v15, v52
	v_fmamk_f32 v15, v15, 0x3a000000, v13
	v_mul_f32_e32 v52, 0x4f800000, v15
	v_cmp_gt_f32_e32 vcc, s18, v15
	s_nop 1
	v_cndmask_b32_e32 v15, v15, v52, vcc
	v_sqrt_f32_e32 v52, v15
	s_nop 0
	v_add_u32_e32 v53, -1, v52
	v_add_u32_e32 v54, 1, v52
	v_fma_f32 v55, -v53, v52, v15
	v_fma_f32 v56, -v54, v52, v15
	v_cmp_ge_f32_e64 s[6:7], 0, v55
	s_nop 1
	v_cndmask_b32_e64 v52, v52, v53, s[6:7]
	v_cmp_lt_f32_e64 s[6:7], 0, v56
	s_nop 1
	v_cndmask_b32_e64 v52, v52, v54, s[6:7]
	v_mul_f32_e32 v53, 0x37800000, v52
	v_cndmask_b32_e32 v52, v52, v53, vcc
	v_cmp_class_f32_e32 vcc, v15, v14
	s_nop 1
	v_cndmask_b32_e32 v15, v52, v15, vcc
	v_div_scale_f32 v52, s[6:7], v15, v15, 1.0
	v_rcp_f32_e32 v54, v52
	v_div_scale_f32 v53, vcc, 1.0, v15, 1.0
	v_fma_f32 v55, -v52, v54, 1.0
	v_fmac_f32_e32 v54, v55, v54
	v_mul_f32_e32 v55, v53, v54
	v_fma_f32 v56, -v52, v55, v53
	v_fmac_f32_e32 v55, v56, v54
	v_fma_f32 v52, -v52, v55, v53
	v_div_fmas_f32 v52, v52, v54, v55
	v_div_fixup_f32 v52, v52, v15, 1.0
	v_pk_mul_f32 v[16:17], v[16:17], v[52:53] op_sel_hi:[1,0]
	v_pk_mul_f32 v[18:19], v[18:19], v[52:53] op_sel_hi:[1,0]
	v_pk_mul_f32 v[16:17], v[100:101], v[16:17]
	v_pk_mul_f32 v[18:19], v[102:103], v[18:19]
	v_cvt_pk_bf16_f32 v16, v16, v17
	v_cvt_pk_bf16_f32 v17, v18, v19
	global_store_dwordx2 v[4:5], v[16:17], off
	v_pk_mul_f32 v[20:21], v[20:21], v[52:53] op_sel_hi:[1,0]
	v_pk_mul_f32 v[22:23], v[22:23], v[52:53] op_sel_hi:[1,0]
	v_pk_mul_f32 v[20:21], v[104:105], v[20:21]
	v_pk_mul_f32 v[22:23], v[106:107], v[22:23]
	v_cvt_pk_bf16_f32 v20, v20, v21
	v_cvt_pk_bf16_f32 v21, v22, v23
	global_store_dwordx2 v[4:5], v[20:21], off offset:512
	v_pk_mul_f32 v[24:25], v[24:25], v[52:53] op_sel_hi:[1,0]
	v_pk_mul_f32 v[26:27], v[26:27], v[52:53] op_sel_hi:[1,0]
	v_pk_mul_f32 v[24:25], v[108:109], v[24:25]
	v_pk_mul_f32 v[26:27], v[110:111], v[26:27]
	v_cvt_pk_bf16_f32 v24, v24, v25
	v_cvt_pk_bf16_f32 v25, v26, v27
	global_store_dwordx2 v[4:5], v[24:25], off offset:1024
	v_pk_mul_f32 v[28:29], v[28:29], v[52:53] op_sel_hi:[1,0]
	v_pk_mul_f32 v[30:31], v[30:31], v[52:53] op_sel_hi:[1,0]
	v_pk_mul_f32 v[28:29], v[112:113], v[28:29]
	v_pk_mul_f32 v[30:31], v[114:115], v[30:31]
	v_cvt_pk_bf16_f32 v28, v28, v29
	v_cvt_pk_bf16_f32 v29, v30, v31
	global_store_dwordx2 v[4:5], v[28:29], off offset:1536
	v_pk_mul_f32 v[36:37], v[36:37], v[52:53] op_sel_hi:[1,0]
	v_pk_mul_f32 v[38:39], v[38:39], v[52:53] op_sel_hi:[1,0]
	v_pk_mul_f32 v[36:37], v[116:117], v[36:37]
	v_pk_mul_f32 v[38:39], v[118:119], v[38:39]
	v_cvt_pk_bf16_f32 v36, v36, v37
	v_cvt_pk_bf16_f32 v37, v38, v39
	global_store_dwordx2 v[4:5], v[36:37], off offset:2048
	v_pk_mul_f32 v[40:41], v[40:41], v[52:53] op_sel_hi:[1,0]
	v_pk_mul_f32 v[42:43], v[42:43], v[52:53] op_sel_hi:[1,0]
	v_pk_mul_f32 v[40:41], v[120:121], v[40:41]
	v_pk_mul_f32 v[42:43], v[122:123], v[42:43]
	v_cvt_pk_bf16_f32 v40, v40, v41
	v_cvt_pk_bf16_f32 v41, v42, v43
	global_store_dwordx2 v[4:5], v[40:41], off offset:2560
	v_pk_mul_f32 v[48:49], v[48:49], v[52:53] op_sel_hi:[1,0]
	v_pk_mul_f32 v[50:51], v[50:51], v[52:53] op_sel_hi:[1,0]
	v_pk_mul_f32 v[48:49], v[124:125], v[48:49]
	v_pk_mul_f32 v[50:51], v[126:127], v[50:51]
	v_cvt_pk_bf16_f32 v48, v48, v49
	v_cvt_pk_bf16_f32 v49, v50, v51
	global_store_dwordx2 v[4:5], v[48:49], off offset:3072
	v_pk_mul_f32 v[44:45], v[44:45], v[52:53] op_sel_hi:[1,0]
	v_pk_mul_f32 v[46:47], v[46:47], v[52:53] op_sel_hi:[1,0]
	v_pk_mul_f32 v[44:45], v[128:129], v[44:45]
	v_pk_mul_f32 v[46:47], v[130:131], v[46:47]
	v_cvt_pk_bf16_f32 v44, v44, v45
	v_cvt_pk_bf16_f32 v45, v46, v47
	global_store_dwordx2 v[4:5], v[44:45], off offset:3584
	v_lshl_add_u64 v[4:5], v[4:5], 0, s[4:5]
	s_cbranch_scc1 .LBB0_85
